# SwiGLU act stores: write-through only on the last two tiles of each up-GEMM phase (plain write-back stores before), on top of v91
# baseline (speedup 1.0000x reference)
;     __device__ __forceinline__ void operator()(const f32x4 (&acc)[2], int srow, int cgp, int kq) const { one(acc[0], srow, 2 * cgp, kq); one(acc[1], srow, 2 * cgp + 1, kq); }
;     __device__ __forceinline__ void operator()(AccRef acc, const pg8::Unit& u, int wr, int wc, int fr, int fq) const {
;         const int row0 = u.pm * 256 + wr * 64 + fr, col0 = u.pn * 128 + wc * 32 + 8 * fq;
; #pragma unroll
;         for (int ai = 0; ai < 2; ++ai)
; #pragma unroll
;             for (int m = 0; m < 4; ++m) {
;                 const int row = row0 + ai * 128 + m * 16;
;                 const float rs = rs_from(ssp + (size_t)row * 16, 4, 1.0f / 1024.0f);
;                 f32x4 o[2];
; #pragma unroll
;                 for (int n = 0; n < 2; ++n)
; #pragma unroll
;                     for (int j = 0; j < 4; ++j) {
;                         const float g = acc[ai][0][m][n][j] * rs, up = acc[ai][1][m][n][j] * rs;
;                         o[n][j] = g * __builtin_amdgcn_rcpf(1.0f + __expf(-g)) * up;
;                     }
;                 *(u32x4*)(act + (size_t)row * FF + col0) = pack8(o[0], o[1]);
.LBB0_376:
.Lswi_beg0:
	s_cmp_lt_u32 s33, 10
	v_add_u32_e32 v249, 0x2000, v247
	global_load_dwordx4 v[154:157], v249, s[46:47]
	global_load_dwordx4 v[158:161], v249, s[46:47] offset:1024
	global_load_dwordx4 v[162:165], v249, s[46:47] offset:2048
	global_load_dwordx4 v[166:169], v249, s[46:47] offset:3072
	v_mbcnt_lo_u32_b32 v170, -1, 0
	v_mbcnt_hi_u32_b32 v170, -1, v170
	v_xor_b32_e32 v171, 16, v170
	v_xor_b32_e32 v172, 32, v170
	v_lshlrev_b32_e32 v171, 2, v171
	v_lshlrev_b32_e32 v172, 2, v172
	v_lshl_or_b32 v173, s61, 7, v148
	v_lshlrev_b32_e32 v173, 1, v173
	v_mad_u32_u24 v248, v246, s51, v173
	s_waitcnt vmcnt(12)
	v_add_f32_e32 v230, v230, v231
	v_add_f32_e32 v232, v232, v233
	v_add_f32_e32 v234, v234, v235
	v_add_f32_e32 v236, v236, v237
	v_add_f32_e32 v238, v238, v239
	v_add_f32_e32 v240, v240, v241
	v_add_f32_e32 v242, v242, v243
	v_add_f32_e32 v244, v244, v245
	v_add_f32_e32 v230, v230, v232
	v_add_f32_e32 v234, v234, v236
	v_add_f32_e32 v238, v238, v240
	v_add_f32_e32 v242, v242, v244
	ds_bpermute_b32 v231, v171, v230
	ds_bpermute_b32 v235, v171, v234
	ds_bpermute_b32 v239, v171, v238
	ds_bpermute_b32 v243, v171, v242
	s_waitcnt lgkmcnt(0)
	v_add_f32_e32 v230, v230, v231
	v_add_f32_e32 v234, v234, v235
	v_add_f32_e32 v238, v238, v239
	v_add_f32_e32 v242, v242, v243
	ds_bpermute_b32 v231, v172, v230
	ds_bpermute_b32 v235, v172, v234
	ds_bpermute_b32 v239, v172, v238
	ds_bpermute_b32 v243, v172, v242
	s_waitcnt lgkmcnt(0)
	v_add_f32_e32 v230, v230, v231
	v_add_f32_e32 v234, v234, v235
	v_add_f32_e32 v238, v238, v239
	v_add_f32_e32 v242, v242, v243
	v_fmamk_f32 v232, v230, 0x3a800000, v152
	v_fmamk_f32 v236, v234, 0x3a800000, v152
	v_fmamk_f32 v240, v238, 0x3a800000, v152
	v_fmamk_f32 v244, v242, 0x3a800000, v152
	v_rsq_f32_e32 v230, v232
	v_rsq_f32_e32 v234, v236
	v_rsq_f32_e32 v238, v240
	v_rsq_f32_e32 v242, v244
	s_nop 0
	v_mul_f32_e32 v230, 0xbfb8aa3b, v230
	v_mul_f32_e32 v234, 0xbfb8aa3b, v234
	v_mul_f32_e32 v238, 0xbfb8aa3b, v238
	v_mul_f32_e32 v242, 0xbfb8aa3b, v242
	v_pk_mul_f32 v[176:177], v[116:117], v[230:231] op_sel_hi:[1,0]
	v_pk_mul_f32 v[178:179], v[118:119], v[230:231] op_sel_hi:[1,0]
	v_pk_mul_f32 v[180:181], v[112:113], v[230:231] op_sel_hi:[1,0]
	v_pk_mul_f32 v[182:183], v[114:115], v[230:231] op_sel_hi:[1,0]
	v_exp_f32_e32 v176, v176
	v_exp_f32_e32 v177, v177
	v_exp_f32_e32 v178, v178
	v_exp_f32_e32 v179, v179
	v_exp_f32_e32 v180, v180
	v_exp_f32_e32 v181, v181
	v_exp_f32_e32 v182, v182
	v_exp_f32_e32 v183, v183
	v_pk_fma_f32 v[176:177], v[176:177], v[232:233], v[232:233] op_sel_hi:[1,0,0]
	v_pk_fma_f32 v[178:179], v[178:179], v[232:233], v[232:233] op_sel_hi:[1,0,0]
	v_pk_fma_f32 v[180:181], v[180:181], v[232:233], v[232:233] op_sel_hi:[1,0,0]
	v_pk_fma_f32 v[182:183], v[182:183], v[232:233], v[232:233] op_sel_hi:[1,0,0]
	v_rcp_f32_e32 v176, v176
	v_rcp_f32_e32 v177, v177
	v_rcp_f32_e32 v178, v178
	v_rcp_f32_e32 v179, v179
	v_rcp_f32_e32 v180, v180
	v_rcp_f32_e32 v181, v181
	v_rcp_f32_e32 v182, v182
	v_rcp_f32_e32 v183, v183
	v_pk_mul_f32 v[116:117], v[116:117], v[124:125]
	v_pk_mul_f32 v[118:119], v[118:119], v[126:127]
	v_pk_mul_f32 v[112:113], v[112:113], v[120:121]
	v_pk_mul_f32 v[114:115], v[114:115], v[122:123]
	v_pk_mul_f32 v[176:177], v[116:117], v[176:177]
	v_pk_mul_f32 v[178:179], v[118:119], v[178:179]
	v_pk_mul_f32 v[180:181], v[112:113], v[180:181]
	v_pk_mul_f32 v[182:183], v[114:115], v[182:183]
	v_cvt_pk_bf16_f32 v192, v176, v177
	v_cvt_pk_bf16_f32 v193, v178, v179
	v_cvt_pk_bf16_f32 v194, v180, v181
	v_cvt_pk_bf16_f32 v195, v182, v183
	v_mov_b32_e32 v200, v248
	s_cbranch_scc1 .Lwtb0_0
	global_store_dwordx4 v200, v[192:195], s[48:49] sc0 sc1
	s_branch .Lwtd0_0
;     __device__ __forceinline__ void operator()(AccRef acc, const pg8::Unit& u, int wr, int wc, int fr, int fq) const {
;     ...
;                 const float rs = rs_from(ssp + (size_t)row * 16, 4, 1.0f / 1024.0f);
;                 f32x4 o[2];
; #pragma unroll
;                 for (int n = 0; n < 2; ++n)
; #pragma unroll
;                     for (int j = 0; j < 4; ++j) {
;                         const float g = acc[ai][0][m][n][j] * rs, up = acc[ai][1][m][n][j] * rs;
;                         o[n][j] = g * __builtin_amdgcn_rcpf(1.0f + __expf(-g)) * up;
;                     }
;                 *(u32x4*)(act + (size_t)row * FF + col0) = pack8(o[0], o[1]);
.Lwtb0_0:
	global_store_dwordx4 v200, v[192:195], s[48:49]
.Lwtd0_0:
	v_pk_mul_f32 v[184:185], v[100:101], v[234:235] op_sel_hi:[1,0]
	v_pk_mul_f32 v[186:187], v[102:103], v[234:235] op_sel_hi:[1,0]
	v_pk_mul_f32 v[188:189], v[96:97], v[234:235] op_sel_hi:[1,0]
	v_pk_mul_f32 v[190:191], v[98:99], v[234:235] op_sel_hi:[1,0]
	v_exp_f32_e32 v184, v184
	v_exp_f32_e32 v185, v185
	v_exp_f32_e32 v186, v186
	v_exp_f32_e32 v187, v187
	v_exp_f32_e32 v188, v188
	v_exp_f32_e32 v189, v189
	v_exp_f32_e32 v190, v190
	v_exp_f32_e32 v191, v191
	v_pk_fma_f32 v[184:185], v[184:185], v[236:237], v[236:237] op_sel_hi:[1,0,0]
	v_pk_fma_f32 v[186:187], v[186:187], v[236:237], v[236:237] op_sel_hi:[1,0,0]
	v_pk_fma_f32 v[188:189], v[188:189], v[236:237], v[236:237] op_sel_hi:[1,0,0]
	v_pk_fma_f32 v[190:191], v[190:191], v[236:237], v[236:237] op_sel_hi:[1,0,0]
	v_rcp_f32_e32 v184, v184
	v_rcp_f32_e32 v185, v185
	v_rcp_f32_e32 v186, v186
	v_rcp_f32_e32 v187, v187
	v_rcp_f32_e32 v188, v188
	v_rcp_f32_e32 v189, v189
	v_rcp_f32_e32 v190, v190
	v_rcp_f32_e32 v191, v191
	v_pk_mul_f32 v[100:101], v[100:101], v[108:109]
	v_pk_mul_f32 v[102:103], v[102:103], v[110:111]
	v_pk_mul_f32 v[96:97], v[96:97], v[104:105]
	v_pk_mul_f32 v[98:99], v[98:99], v[106:107]
	v_pk_mul_f32 v[184:185], v[100:101], v[184:185]
	v_pk_mul_f32 v[186:187], v[102:103], v[186:187]
	v_pk_mul_f32 v[188:189], v[96:97], v[188:189]
	v_pk_mul_f32 v[190:191], v[98:99], v[190:191]
	v_cvt_pk_bf16_f32 v196, v184, v185
	v_cvt_pk_bf16_f32 v197, v186, v187
	v_cvt_pk_bf16_f32 v198, v188, v189
	v_cvt_pk_bf16_f32 v199, v190, v191
	v_add_u32_e32 v201, 0x16000, v248
	s_cbranch_scc1 .Lwtb0_1
	global_store_dwordx4 v201, v[196:199], s[48:49] sc0 sc1
	s_branch .Lwtd0_1
.Lwtb0_1:
	global_store_dwordx4 v201, v[196:199], s[48:49]
.Lwtd0_1:
	v_pk_mul_f32 v[176:177], v[84:85], v[238:239] op_sel_hi:[1,0]
	v_pk_mul_f32 v[178:179], v[86:87], v[238:239] op_sel_hi:[1,0]
	v_pk_mul_f32 v[180:181], v[80:81], v[238:239] op_sel_hi:[1,0]
	v_pk_mul_f32 v[182:183], v[82:83], v[238:239] op_sel_hi:[1,0]
	v_exp_f32_e32 v176, v176
	v_exp_f32_e32 v177, v177
	v_exp_f32_e32 v178, v178
	v_exp_f32_e32 v179, v179
	v_exp_f32_e32 v180, v180
	v_exp_f32_e32 v181, v181
	v_exp_f32_e32 v182, v182
	v_exp_f32_e32 v183, v183
	v_pk_fma_f32 v[176:177], v[176:177], v[240:241], v[240:241] op_sel_hi:[1,0,0]
	v_pk_fma_f32 v[178:179], v[178:179], v[240:241], v[240:241] op_sel_hi:[1,0,0]
	v_pk_fma_f32 v[180:181], v[180:181], v[240:241], v[240:241] op_sel_hi:[1,0,0]
	v_pk_fma_f32 v[182:183], v[182:183], v[240:241], v[240:241] op_sel_hi:[1,0,0]
	v_rcp_f32_e32 v176, v176
	v_rcp_f32_e32 v177, v177
	v_rcp_f32_e32 v178, v178
	v_rcp_f32_e32 v179, v179
	v_rcp_f32_e32 v180, v180
	v_rcp_f32_e32 v181, v181
	v_rcp_f32_e32 v182, v182
	v_rcp_f32_e32 v183, v183
	v_pk_mul_f32 v[84:85], v[84:85], v[92:93]
	v_pk_mul_f32 v[86:87], v[86:87], v[94:95]
	v_pk_mul_f32 v[80:81], v[80:81], v[88:89]
	v_pk_mul_f32 v[82:83], v[82:83], v[90:91]
	v_pk_mul_f32 v[176:177], v[84:85], v[176:177]
	v_pk_mul_f32 v[178:179], v[86:87], v[178:179]
	v_pk_mul_f32 v[180:181], v[80:81], v[180:181]
	v_pk_mul_f32 v[182:183], v[82:83], v[182:183]
	v_cvt_pk_bf16_f32 v192, v176, v177
	v_cvt_pk_bf16_f32 v193, v178, v179
	v_cvt_pk_bf16_f32 v194, v180, v181
	v_cvt_pk_bf16_f32 v195, v182, v183
	v_add_u32_e32 v200, 0x2c000, v248
	s_cbranch_scc1 .Lwtb0_2
	global_store_dwordx4 v200, v[192:195], s[48:49] sc0 sc1
	s_branch .Lwtd0_2

;     __device__ __forceinline__ void operator()(AccRef acc, const pg8::Unit& u, int wr, int wc, int fr, int fq) const {
;     ...
;                 const float rs = rs_from(ssp + (size_t)row * 16, 4, 1.0f / 1024.0f);
;                 f32x4 o[2];
; #pragma unroll
;                 for (int n = 0; n < 2; ++n)
; #pragma unroll
;                     for (int j = 0; j < 4; ++j) {
;                         const float g = acc[ai][0][m][n][j] * rs, up = acc[ai][1][m][n][j] * rs;
;                         o[n][j] = g * __builtin_amdgcn_rcpf(1.0f + __expf(-g)) * up;
;                     }
;                 *(u32x4*)(act + (size_t)row * FF + col0) = pack8(o[0], o[1]);
.Lwtd0_2:
	v_pk_mul_f32 v[184:185], v[68:69], v[242:243] op_sel_hi:[1,0]
	v_pk_mul_f32 v[186:187], v[70:71], v[242:243] op_sel_hi:[1,0]
	v_pk_mul_f32 v[188:189], v[64:65], v[242:243] op_sel_hi:[1,0]
	v_pk_mul_f32 v[190:191], v[66:67], v[242:243] op_sel_hi:[1,0]
	v_exp_f32_e32 v184, v184
	v_exp_f32_e32 v185, v185
	v_exp_f32_e32 v186, v186
	v_exp_f32_e32 v187, v187
	v_exp_f32_e32 v188, v188
	v_exp_f32_e32 v189, v189
	v_exp_f32_e32 v190, v190
	v_exp_f32_e32 v191, v191
	v_pk_fma_f32 v[184:185], v[184:185], v[244:245], v[244:245] op_sel_hi:[1,0,0]
	v_pk_fma_f32 v[186:187], v[186:187], v[244:245], v[244:245] op_sel_hi:[1,0,0]
	v_pk_fma_f32 v[188:189], v[188:189], v[244:245], v[244:245] op_sel_hi:[1,0,0]
	v_pk_fma_f32 v[190:191], v[190:191], v[244:245], v[244:245] op_sel_hi:[1,0,0]
	v_rcp_f32_e32 v184, v184
	v_rcp_f32_e32 v185, v185
	v_rcp_f32_e32 v186, v186
	v_rcp_f32_e32 v187, v187
	v_rcp_f32_e32 v188, v188
	v_rcp_f32_e32 v189, v189
	v_rcp_f32_e32 v190, v190
	v_rcp_f32_e32 v191, v191
	v_pk_mul_f32 v[68:69], v[68:69], v[76:77]
	v_pk_mul_f32 v[70:71], v[70:71], v[78:79]
	v_pk_mul_f32 v[64:65], v[64:65], v[72:73]
	v_pk_mul_f32 v[66:67], v[66:67], v[74:75]
	v_pk_mul_f32 v[184:185], v[68:69], v[184:185]
	v_pk_mul_f32 v[186:187], v[70:71], v[186:187]
	v_pk_mul_f32 v[188:189], v[64:65], v[188:189]
	v_pk_mul_f32 v[190:191], v[66:67], v[190:191]
	v_cvt_pk_bf16_f32 v196, v184, v185
	v_cvt_pk_bf16_f32 v197, v186, v187
	v_cvt_pk_bf16_f32 v198, v188, v189
	v_cvt_pk_bf16_f32 v199, v190, v191
	v_add_u32_e32 v201, 0x42000, v248
	s_cbranch_scc1 .Lwtb0_3
	global_store_dwordx4 v201, v[196:199], s[48:49] sc0 sc1
	s_branch .Lwtd0_3

;     __device__ __forceinline__ void operator()(AccRef acc, const pg8::Unit& u, int wr, int wc, int fr, int fq) const {
;     ...
;                 const int row = row0 + ai * 128 + m * 16;
;                 const float rs = rs_from(ssp + (size_t)row * 16, 4, 1.0f / 1024.0f);
;                 f32x4 o[2];
; #pragma unroll
;                 for (int n = 0; n < 2; ++n)
; #pragma unroll
;                     for (int j = 0; j < 4; ++j) {
;                         const float g = acc[ai][0][m][n][j] * rs, up = acc[ai][1][m][n][j] * rs;
;                         o[n][j] = g * __builtin_amdgcn_rcpf(1.0f + __expf(-g)) * up;
;                     }
;                 *(u32x4*)(act + (size_t)row * FF + col0) = pack8(o[0], o[1]);
.Lwtd0_3:
	s_waitcnt vmcnt(4)
	v_add_f32_e32 v154, v154, v155
	v_add_f32_e32 v156, v156, v157
	v_add_f32_e32 v158, v158, v159
	v_add_f32_e32 v160, v160, v161
	v_add_f32_e32 v162, v162, v163
	v_add_f32_e32 v164, v164, v165
	v_add_f32_e32 v166, v166, v167
	v_add_f32_e32 v168, v168, v169
	v_add_f32_e32 v154, v154, v156
	v_add_f32_e32 v158, v158, v160
	v_add_f32_e32 v162, v162, v164
	v_add_f32_e32 v166, v166, v168
	ds_bpermute_b32 v155, v171, v154
	ds_bpermute_b32 v159, v171, v158
	ds_bpermute_b32 v163, v171, v162
	ds_bpermute_b32 v167, v171, v166
	s_waitcnt lgkmcnt(0)
	v_add_f32_e32 v154, v154, v155
	v_add_f32_e32 v158, v158, v159
	v_add_f32_e32 v162, v162, v163
	v_add_f32_e32 v166, v166, v167
	ds_bpermute_b32 v155, v172, v154
	ds_bpermute_b32 v159, v172, v158
	ds_bpermute_b32 v163, v172, v162
	ds_bpermute_b32 v167, v172, v166
	s_waitcnt lgkmcnt(0)
	v_add_f32_e32 v154, v154, v155
	v_add_f32_e32 v158, v158, v159
	v_add_f32_e32 v162, v162, v163
	v_add_f32_e32 v166, v166, v167
	v_fmamk_f32 v156, v154, 0x3a800000, v152
	v_fmamk_f32 v160, v158, 0x3a800000, v152
	v_fmamk_f32 v164, v162, 0x3a800000, v152
	v_fmamk_f32 v168, v166, 0x3a800000, v152
	v_rsq_f32_e32 v154, v156
	v_rsq_f32_e32 v158, v160
	v_rsq_f32_e32 v162, v164
	v_rsq_f32_e32 v166, v168
	s_nop 0
	v_mul_f32_e32 v154, 0xbfb8aa3b, v154
	v_mul_f32_e32 v158, 0xbfb8aa3b, v158
	v_mul_f32_e32 v162, 0xbfb8aa3b, v162
	v_mul_f32_e32 v166, 0xbfb8aa3b, v166
	v_pk_mul_f32 v[176:177], v[52:53], v[154:155] op_sel_hi:[1,0]
	v_pk_mul_f32 v[178:179], v[54:55], v[154:155] op_sel_hi:[1,0]
	v_pk_mul_f32 v[180:181], v[48:49], v[154:155] op_sel_hi:[1,0]
	v_pk_mul_f32 v[182:183], v[50:51], v[154:155] op_sel_hi:[1,0]
	v_exp_f32_e32 v176, v176
	v_exp_f32_e32 v177, v177
	v_exp_f32_e32 v178, v178
	v_exp_f32_e32 v179, v179
	v_exp_f32_e32 v180, v180
	v_exp_f32_e32 v181, v181
	v_exp_f32_e32 v182, v182
	v_exp_f32_e32 v183, v183
	v_pk_fma_f32 v[176:177], v[176:177], v[156:157], v[156:157] op_sel_hi:[1,0,0]
	v_pk_fma_f32 v[178:179], v[178:179], v[156:157], v[156:157] op_sel_hi:[1,0,0]
	v_pk_fma_f32 v[180:181], v[180:181], v[156:157], v[156:157] op_sel_hi:[1,0,0]
	v_pk_fma_f32 v[182:183], v[182:183], v[156:157], v[156:157] op_sel_hi:[1,0,0]
	v_rcp_f32_e32 v176, v176
	v_rcp_f32_e32 v177, v177
	v_rcp_f32_e32 v178, v178
	v_rcp_f32_e32 v179, v179
	v_rcp_f32_e32 v180, v180
	v_rcp_f32_e32 v181, v181
	v_rcp_f32_e32 v182, v182
	v_rcp_f32_e32 v183, v183
	v_pk_mul_f32 v[52:53], v[52:53], v[60:61]
	v_pk_mul_f32 v[54:55], v[54:55], v[62:63]
	v_pk_mul_f32 v[48:49], v[48:49], v[56:57]
	v_pk_mul_f32 v[50:51], v[50:51], v[58:59]
	v_pk_mul_f32 v[176:177], v[52:53], v[176:177]
	v_pk_mul_f32 v[178:179], v[54:55], v[178:179]
	v_pk_mul_f32 v[180:181], v[48:49], v[180:181]
	v_pk_mul_f32 v[182:183], v[50:51], v[182:183]
	v_cvt_pk_bf16_f32 v192, v176, v177
	v_cvt_pk_bf16_f32 v193, v178, v179
	v_cvt_pk_bf16_f32 v194, v180, v181
	v_cvt_pk_bf16_f32 v195, v182, v183
	v_add_u32_e32 v200, 0xb0000, v248
	s_cbranch_scc1 .Lwtb0_4
	global_store_dwordx4 v200, v[192:195], s[48:49] sc0 sc1
	s_branch .Lwtd0_4

;     __device__ __forceinline__ void operator()(AccRef acc, const pg8::Unit& u, int wr, int wc, int fr, int fq) const {
;     ...
;                 const float rs = rs_from(ssp + (size_t)row * 16, 4, 1.0f / 1024.0f);
;                 f32x4 o[2];
; #pragma unroll
;                 for (int n = 0; n < 2; ++n)
; #pragma unroll
;                     for (int j = 0; j < 4; ++j) {
;                         const float g = acc[ai][0][m][n][j] * rs, up = acc[ai][1][m][n][j] * rs;
;                         o[n][j] = g * __builtin_amdgcn_rcpf(1.0f + __expf(-g)) * up;
;                     }
;                 *(u32x4*)(act + (size_t)row * FF + col0) = pack8(o[0], o[1]);
.Lwtd0_4:
	v_pk_mul_f32 v[184:185], v[36:37], v[158:159] op_sel_hi:[1,0]
	v_pk_mul_f32 v[186:187], v[38:39], v[158:159] op_sel_hi:[1,0]
	v_pk_mul_f32 v[188:189], v[32:33], v[158:159] op_sel_hi:[1,0]
	v_pk_mul_f32 v[190:191], v[34:35], v[158:159] op_sel_hi:[1,0]
	v_exp_f32_e32 v184, v184
	v_exp_f32_e32 v185, v185
	v_exp_f32_e32 v186, v186
	v_exp_f32_e32 v187, v187
	v_exp_f32_e32 v188, v188
	v_exp_f32_e32 v189, v189
	v_exp_f32_e32 v190, v190
	v_exp_f32_e32 v191, v191
	v_pk_fma_f32 v[184:185], v[184:185], v[160:161], v[160:161] op_sel_hi:[1,0,0]
	v_pk_fma_f32 v[186:187], v[186:187], v[160:161], v[160:161] op_sel_hi:[1,0,0]
	v_pk_fma_f32 v[188:189], v[188:189], v[160:161], v[160:161] op_sel_hi:[1,0,0]
	v_pk_fma_f32 v[190:191], v[190:191], v[160:161], v[160:161] op_sel_hi:[1,0,0]
	v_rcp_f32_e32 v184, v184
	v_rcp_f32_e32 v185, v185
	v_rcp_f32_e32 v186, v186
	v_rcp_f32_e32 v187, v187
	v_rcp_f32_e32 v188, v188
	v_rcp_f32_e32 v189, v189
	v_rcp_f32_e32 v190, v190
	v_rcp_f32_e32 v191, v191
	v_pk_mul_f32 v[36:37], v[36:37], v[44:45]
	v_pk_mul_f32 v[38:39], v[38:39], v[46:47]
	v_pk_mul_f32 v[32:33], v[32:33], v[40:41]
	v_pk_mul_f32 v[34:35], v[34:35], v[42:43]
	v_pk_mul_f32 v[184:185], v[36:37], v[184:185]
	v_pk_mul_f32 v[186:187], v[38:39], v[186:187]
	v_pk_mul_f32 v[188:189], v[32:33], v[188:189]
	v_pk_mul_f32 v[190:191], v[34:35], v[190:191]
	v_cvt_pk_bf16_f32 v196, v184, v185
	v_cvt_pk_bf16_f32 v197, v186, v187
	v_cvt_pk_bf16_f32 v198, v188, v189
	v_cvt_pk_bf16_f32 v199, v190, v191
	v_add_u32_e32 v201, 0xc6000, v248
	s_cbranch_scc1 .Lwtb0_5
	global_store_dwordx4 v201, v[196:199], s[48:49] sc0 sc1
	s_branch .Lwtd0_5

;     __device__ __forceinline__ void operator()(AccRef acc, const pg8::Unit& u, int wr, int wc, int fr, int fq) const {
;     ...
;                 const float rs = rs_from(ssp + (size_t)row * 16, 4, 1.0f / 1024.0f);
;                 f32x4 o[2];
; #pragma unroll
;                 for (int n = 0; n < 2; ++n)
; #pragma unroll
;                     for (int j = 0; j < 4; ++j) {
;                         const float g = acc[ai][0][m][n][j] * rs, up = acc[ai][1][m][n][j] * rs;
;                         o[n][j] = g * __builtin_amdgcn_rcpf(1.0f + __expf(-g)) * up;
;                     }
;                 *(u32x4*)(act + (size_t)row * FF + col0) = pack8(o[0], o[1]);
.Lwtd0_5:
	v_pk_mul_f32 v[176:177], v[20:21], v[162:163] op_sel_hi:[1,0]
	v_pk_mul_f32 v[178:179], v[22:23], v[162:163] op_sel_hi:[1,0]
	v_pk_mul_f32 v[180:181], v[16:17], v[162:163] op_sel_hi:[1,0]
	v_pk_mul_f32 v[182:183], v[18:19], v[162:163] op_sel_hi:[1,0]
	v_exp_f32_e32 v176, v176
	v_exp_f32_e32 v177, v177
	v_exp_f32_e32 v178, v178
	v_exp_f32_e32 v179, v179
	v_exp_f32_e32 v180, v180
	v_exp_f32_e32 v181, v181
	v_exp_f32_e32 v182, v182
	v_exp_f32_e32 v183, v183
	v_pk_fma_f32 v[176:177], v[176:177], v[164:165], v[164:165] op_sel_hi:[1,0,0]
	v_pk_fma_f32 v[178:179], v[178:179], v[164:165], v[164:165] op_sel_hi:[1,0,0]
	v_pk_fma_f32 v[180:181], v[180:181], v[164:165], v[164:165] op_sel_hi:[1,0,0]
	v_pk_fma_f32 v[182:183], v[182:183], v[164:165], v[164:165] op_sel_hi:[1,0,0]
	v_rcp_f32_e32 v176, v176
	v_rcp_f32_e32 v177, v177
	v_rcp_f32_e32 v178, v178
	v_rcp_f32_e32 v179, v179
	v_rcp_f32_e32 v180, v180
	v_rcp_f32_e32 v181, v181
	v_rcp_f32_e32 v182, v182
	v_rcp_f32_e32 v183, v183
	v_pk_mul_f32 v[20:21], v[20:21], v[28:29]
	v_pk_mul_f32 v[22:23], v[22:23], v[30:31]
	v_pk_mul_f32 v[16:17], v[16:17], v[24:25]
	v_pk_mul_f32 v[18:19], v[18:19], v[26:27]
	v_pk_mul_f32 v[176:177], v[20:21], v[176:177]
	v_pk_mul_f32 v[178:179], v[22:23], v[178:179]
	v_pk_mul_f32 v[180:181], v[16:17], v[180:181]
	v_pk_mul_f32 v[182:183], v[18:19], v[182:183]
	v_cvt_pk_bf16_f32 v192, v176, v177
	v_cvt_pk_bf16_f32 v193, v178, v179
	v_cvt_pk_bf16_f32 v194, v180, v181
	v_cvt_pk_bf16_f32 v195, v182, v183
	v_add_u32_e32 v200, 0xdc000, v248
	s_cbranch_scc1 .Lwtb0_6
	global_store_dwordx4 v200, v[192:195], s[48:49] sc0 sc1
	s_branch .Lwtd0_6

;     __device__ __forceinline__ void operator()(AccRef acc, const pg8::Unit& u, int wr, int wc, int fr, int fq) const {
;     ...
;                 const float rs = rs_from(ssp + (size_t)row * 16, 4, 1.0f / 1024.0f);
;                 f32x4 o[2];
; #pragma unroll
;                 for (int n = 0; n < 2; ++n)
; #pragma unroll
;                     for (int j = 0; j < 4; ++j) {
;                         const float g = acc[ai][0][m][n][j] * rs, up = acc[ai][1][m][n][j] * rs;
;                         o[n][j] = g * __builtin_amdgcn_rcpf(1.0f + __expf(-g)) * up;
;                     }
;                 *(u32x4*)(act + (size_t)row * FF + col0) = pack8(o[0], o[1]);
.Lwtd0_6:
	v_pk_mul_f32 v[184:185], v[4:5], v[166:167] op_sel_hi:[1,0]
	v_pk_mul_f32 v[186:187], v[6:7], v[166:167] op_sel_hi:[1,0]
	v_pk_mul_f32 v[188:189], v[0:1], v[166:167] op_sel_hi:[1,0]
	v_pk_mul_f32 v[190:191], v[2:3], v[166:167] op_sel_hi:[1,0]
	v_exp_f32_e32 v184, v184
	v_exp_f32_e32 v185, v185
	v_exp_f32_e32 v186, v186
	v_exp_f32_e32 v187, v187
	v_exp_f32_e32 v188, v188
	v_exp_f32_e32 v189, v189
	v_exp_f32_e32 v190, v190
	v_exp_f32_e32 v191, v191
	v_pk_fma_f32 v[184:185], v[184:185], v[168:169], v[168:169] op_sel_hi:[1,0,0]
	v_pk_fma_f32 v[186:187], v[186:187], v[168:169], v[168:169] op_sel_hi:[1,0,0]
	v_pk_fma_f32 v[188:189], v[188:189], v[168:169], v[168:169] op_sel_hi:[1,0,0]
	v_pk_fma_f32 v[190:191], v[190:191], v[168:169], v[168:169] op_sel_hi:[1,0,0]
	v_rcp_f32_e32 v184, v184
	v_rcp_f32_e32 v185, v185
	v_rcp_f32_e32 v186, v186
	v_rcp_f32_e32 v187, v187
	v_rcp_f32_e32 v188, v188
	v_rcp_f32_e32 v189, v189
	v_rcp_f32_e32 v190, v190
	v_rcp_f32_e32 v191, v191
	v_pk_mul_f32 v[4:5], v[4:5], v[12:13]
	v_pk_mul_f32 v[6:7], v[6:7], v[14:15]
	v_pk_mul_f32 v[0:1], v[0:1], v[8:9]
	v_pk_mul_f32 v[2:3], v[2:3], v[10:11]
	v_pk_mul_f32 v[184:185], v[4:5], v[184:185]
	v_pk_mul_f32 v[186:187], v[6:7], v[186:187]
	v_pk_mul_f32 v[188:189], v[0:1], v[188:189]
	v_pk_mul_f32 v[190:191], v[2:3], v[190:191]
	v_cvt_pk_bf16_f32 v196, v184, v185
	v_cvt_pk_bf16_f32 v197, v186, v187
	v_cvt_pk_bf16_f32 v198, v188, v189
	v_cvt_pk_bf16_f32 v199, v190, v191
	v_add_u32_e32 v201, 0xf2000, v248
	s_cbranch_scc1 .Lwtb0_7
	global_store_dwordx4 v201, v[196:199], s[48:49] sc0 sc1
	s_branch .Lwtd0_7

; #define PG8_BAR __builtin_amdgcn_s_barrier()
; template <class Epi, class Sched, bool ALIGN_EPI = false, bool SP2 = false>
; __device__ __forceinline__ void gemm_phase(PG8_LAS unsigned char* lds, const Gemm g, const Sched& S, const Epi& E) {
;     ...
;         if constexpr (ALIGN_EPI) { if (wr == 0) PG8_BAR; }
;         if constexpr (!Epi::AFTER_DRAIN) { E(acc, cur, wr, wc, fr, fq); S.done(cur); }
;         if (!has_next) break;
; #pragma unroll
;         for (int a = 0; a < 2; ++a)
; #pragma unroll
;             for (int b = 0; b < 2; ++b)
; #pragma unroll
;                 for (int m = 0; m < 4; ++m)
; #pragma unroll
;                     for (int n = 0; n < 2; ++n) acc[a][b][m][n] = (f32x4){0.f, 0.f, 0.f, 0.f};
;         cur = nxt; cA = nA; cB = nB; ++ui;
;         if constexpr (ALIGN_EPI) { if (wr == 1) PG8_BAR; }
;     }
.Lwtd0_7:
.Lswi_end0:
	s_and_b64 vcc, exec, s[2:3]
	s_mov_b64 s[2:3], -1
	s_cbranch_vccnz .LBB0_364
	s_andn2_b64 vcc, exec, s[10:11]
	s_cbranch_vccnz .LBB0_363
	s_barrier
	s_branch .LBB0_363

;     __device__ __forceinline__ void operator()(const f32x4 (&acc)[2], int srow, int cgp, int kq) const { one(acc[0], srow, 2 * cgp, kq); one(acc[1], srow, 2 * cgp + 1, kq); }
;     __device__ __forceinline__ void operator()(AccRef acc, const pg8::Unit& u, int wr, int wc, int fr, int fq) const {
;         const int row0 = u.pm * 256 + wr * 64 + fr, col0 = u.pn * 128 + wc * 32 + 8 * fq;
; #pragma unroll
;         for (int ai = 0; ai < 2; ++ai)
; #pragma unroll
;             for (int m = 0; m < 4; ++m) {
;                 const int row = row0 + ai * 128 + m * 16;
;                 const float rs = rs_from(ssp + (size_t)row * 16, 4, 1.0f / 1024.0f);
;                 f32x4 o[2];
; #pragma unroll
;                 for (int n = 0; n < 2; ++n)
; #pragma unroll
;                     for (int j = 0; j < 4; ++j) {
;                         const float g = acc[ai][0][m][n][j] * rs, up = acc[ai][1][m][n][j] * rs;
;                         o[n][j] = g * __builtin_amdgcn_rcpf(1.0f + __expf(-g)) * up;
;                     }
;                 *(u32x4*)(act + (size_t)row * FF + col0) = pack8(o[0], o[1]);
.LBB0_1320:
.Lswi_beg1:
	s_cmp_lt_u32 s35, 10
	v_add_u32_e32 v249, 0x2000, v247
	global_load_dwordx4 v[154:157], v249, s[46:47]
	global_load_dwordx4 v[158:161], v249, s[46:47] offset:1024
	global_load_dwordx4 v[162:165], v249, s[46:47] offset:2048
	global_load_dwordx4 v[166:169], v249, s[46:47] offset:3072
	v_mbcnt_lo_u32_b32 v170, -1, 0
	v_mbcnt_hi_u32_b32 v170, -1, v170
	v_xor_b32_e32 v171, 16, v170
	v_xor_b32_e32 v172, 32, v170
	v_lshlrev_b32_e32 v171, 2, v171
	v_lshlrev_b32_e32 v172, 2, v172
	v_lshl_or_b32 v173, s61, 7, v148
	v_lshlrev_b32_e32 v173, 1, v173
	v_mad_u32_u24 v248, v246, s57, v173
	s_waitcnt vmcnt(12)
	v_add_f32_e32 v230, v230, v231
	v_add_f32_e32 v232, v232, v233
	v_add_f32_e32 v234, v234, v235
	v_add_f32_e32 v236, v236, v237
	v_add_f32_e32 v238, v238, v239
	v_add_f32_e32 v240, v240, v241
	v_add_f32_e32 v242, v242, v243
	v_add_f32_e32 v244, v244, v245
	v_add_f32_e32 v230, v230, v232
	v_add_f32_e32 v234, v234, v236
	v_add_f32_e32 v238, v238, v240
	v_add_f32_e32 v242, v242, v244
	ds_bpermute_b32 v231, v171, v230
	ds_bpermute_b32 v235, v171, v234
	ds_bpermute_b32 v239, v171, v238
	ds_bpermute_b32 v243, v171, v242
	s_waitcnt lgkmcnt(0)
	v_add_f32_e32 v230, v230, v231
	v_add_f32_e32 v234, v234, v235
	v_add_f32_e32 v238, v238, v239
	v_add_f32_e32 v242, v242, v243
	ds_bpermute_b32 v231, v172, v230
	ds_bpermute_b32 v235, v172, v234
	ds_bpermute_b32 v239, v172, v238
	ds_bpermute_b32 v243, v172, v242
	s_waitcnt lgkmcnt(0)
	v_add_f32_e32 v230, v230, v231
	v_add_f32_e32 v234, v234, v235
	v_add_f32_e32 v238, v238, v239
	v_add_f32_e32 v242, v242, v243
	v_fmamk_f32 v232, v230, 0x3a800000, v152
	v_fmamk_f32 v236, v234, 0x3a800000, v152
	v_fmamk_f32 v240, v238, 0x3a800000, v152
	v_fmamk_f32 v244, v242, 0x3a800000, v152
	v_rsq_f32_e32 v230, v232
	v_rsq_f32_e32 v234, v236
	v_rsq_f32_e32 v238, v240
	v_rsq_f32_e32 v242, v244
	s_nop 0
	v_mul_f32_e32 v230, 0xbfb8aa3b, v230
	v_mul_f32_e32 v234, 0xbfb8aa3b, v234
	v_mul_f32_e32 v238, 0xbfb8aa3b, v238
	v_mul_f32_e32 v242, 0xbfb8aa3b, v242
	v_pk_mul_f32 v[176:177], v[116:117], v[230:231] op_sel_hi:[1,0]
	v_pk_mul_f32 v[178:179], v[118:119], v[230:231] op_sel_hi:[1,0]
	v_pk_mul_f32 v[180:181], v[112:113], v[230:231] op_sel_hi:[1,0]
	v_pk_mul_f32 v[182:183], v[114:115], v[230:231] op_sel_hi:[1,0]
	v_exp_f32_e32 v176, v176
	v_exp_f32_e32 v177, v177
	v_exp_f32_e32 v178, v178
	v_exp_f32_e32 v179, v179
	v_exp_f32_e32 v180, v180
	v_exp_f32_e32 v181, v181
	v_exp_f32_e32 v182, v182
	v_exp_f32_e32 v183, v183
	v_pk_fma_f32 v[176:177], v[176:177], v[232:233], v[232:233] op_sel_hi:[1,0,0]
	v_pk_fma_f32 v[178:179], v[178:179], v[232:233], v[232:233] op_sel_hi:[1,0,0]
	v_pk_fma_f32 v[180:181], v[180:181], v[232:233], v[232:233] op_sel_hi:[1,0,0]
	v_pk_fma_f32 v[182:183], v[182:183], v[232:233], v[232:233] op_sel_hi:[1,0,0]
	v_rcp_f32_e32 v176, v176
	v_rcp_f32_e32 v177, v177
	v_rcp_f32_e32 v178, v178
	v_rcp_f32_e32 v179, v179
	v_rcp_f32_e32 v180, v180
	v_rcp_f32_e32 v181, v181
	v_rcp_f32_e32 v182, v182
	v_rcp_f32_e32 v183, v183
	v_pk_mul_f32 v[116:117], v[116:117], v[124:125]
	v_pk_mul_f32 v[118:119], v[118:119], v[126:127]
	v_pk_mul_f32 v[112:113], v[112:113], v[120:121]
	v_pk_mul_f32 v[114:115], v[114:115], v[122:123]
	v_pk_mul_f32 v[176:177], v[116:117], v[176:177]
	v_pk_mul_f32 v[178:179], v[118:119], v[178:179]
	v_pk_mul_f32 v[180:181], v[112:113], v[180:181]
	v_pk_mul_f32 v[182:183], v[114:115], v[182:183]
	v_cvt_pk_bf16_f32 v192, v176, v177
	v_cvt_pk_bf16_f32 v193, v178, v179
	v_cvt_pk_bf16_f32 v194, v180, v181
	v_cvt_pk_bf16_f32 v195, v182, v183
	v_mov_b32_e32 v200, v248
	s_cbranch_scc1 .Lwtb1_0
	global_store_dwordx4 v200, v[192:195], s[48:49] sc0 sc1
	s_branch .Lwtd1_0

; #define PG8_BAR __builtin_amdgcn_s_barrier()
; template <class Epi, class Sched, bool ALIGN_EPI = false, bool SP2 = false>
; __device__ __forceinline__ void gemm_phase(PG8_LAS unsigned char* lds, const Gemm g, const Sched& S, const Epi& E) {
;     ...
;         if constexpr (ALIGN_EPI) { if (wr == 0) PG8_BAR; }
;         if constexpr (!Epi::AFTER_DRAIN) { E(acc, cur, wr, wc, fr, fq); S.done(cur); }
;         if (!has_next) break;
; #pragma unroll
;         for (int a = 0; a < 2; ++a)
; #pragma unroll
;             for (int b = 0; b < 2; ++b)
; #pragma unroll
;                 for (int m = 0; m < 4; ++m)
; #pragma unroll
;                     for (int n = 0; n < 2; ++n) acc[a][b][m][n] = (f32x4){0.f, 0.f, 0.f, 0.f};
;         cur = nxt; cA = nA; cB = nB; ++ui;
;         if constexpr (ALIGN_EPI) { if (wr == 1) PG8_BAR; }
;     }
.Lwtd1_7:
.Lswi_end1:
	s_and_b64 vcc, exec, s[2:3]
	s_mov_b64 s[2:3], -1
	s_cbranch_vccnz .LBB0_1308
	s_andn2_b64 vcc, exec, s[12:13]
	s_cbranch_vccnz .LBB0_1307
	s_barrier
	s_branch .LBB0_1307

;     __device__ __forceinline__ void operator()(const f32x4 (&acc)[2], int srow, int cgp, int kq) const { one(acc[0], srow, 2 * cgp, kq); one(acc[1], srow, 2 * cgp + 1, kq); }
;     __device__ __forceinline__ void operator()(AccRef acc, const pg8::Unit& u, int wr, int wc, int fr, int fq) const {
;         const int row0 = u.pm * 256 + wr * 64 + fr, col0 = u.pn * 128 + wc * 32 + 8 * fq;
; #pragma unroll
;         for (int ai = 0; ai < 2; ++ai)
; #pragma unroll
;             for (int m = 0; m < 4; ++m) {
;                 const int row = row0 + ai * 128 + m * 16;
;                 const float rs = rs_from(ssp + (size_t)row * 16, 4, 1.0f / 1024.0f);
;                 f32x4 o[2];
; #pragma unroll
;                 for (int n = 0; n < 2; ++n)
; #pragma unroll
;                     for (int j = 0; j < 4; ++j) {
;                         const float g = acc[ai][0][m][n][j] * rs, up = acc[ai][1][m][n][j] * rs;
;                         o[n][j] = g * __builtin_amdgcn_rcpf(1.0f + __expf(-g)) * up;
;                     }
;                 *(u32x4*)(act + (size_t)row * FF + col0) = pack8(o[0], o[1]);
.LBB0_2484:
.Lswi_beg3:
	s_cmp_lt_u32 s35, 10
	v_add_u32_e32 v249, 0x2000, v247
	global_load_dwordx4 v[154:157], v249, s[46:47]
	global_load_dwordx4 v[158:161], v249, s[46:47] offset:1024
	global_load_dwordx4 v[162:165], v249, s[46:47] offset:2048
	global_load_dwordx4 v[166:169], v249, s[46:47] offset:3072
	v_mbcnt_lo_u32_b32 v170, -1, 0
	v_mbcnt_hi_u32_b32 v170, -1, v170
	v_xor_b32_e32 v171, 16, v170
	v_xor_b32_e32 v172, 32, v170
	v_lshlrev_b32_e32 v171, 2, v171
	v_lshlrev_b32_e32 v172, 2, v172
	v_lshl_or_b32 v173, s59, 7, v148
	v_lshlrev_b32_e32 v173, 1, v173
	v_mad_u32_u24 v248, v246, s51, v173
	s_waitcnt vmcnt(12)
	v_add_f32_e32 v230, v230, v231
	v_add_f32_e32 v232, v232, v233
	v_add_f32_e32 v234, v234, v235
	v_add_f32_e32 v236, v236, v237
	v_add_f32_e32 v238, v238, v239
	v_add_f32_e32 v240, v240, v241
	v_add_f32_e32 v242, v242, v243
	v_add_f32_e32 v244, v244, v245
	v_add_f32_e32 v230, v230, v232
	v_add_f32_e32 v234, v234, v236
	v_add_f32_e32 v238, v238, v240
	v_add_f32_e32 v242, v242, v244
	ds_bpermute_b32 v231, v171, v230
	ds_bpermute_b32 v235, v171, v234
	ds_bpermute_b32 v239, v171, v238
	ds_bpermute_b32 v243, v171, v242
	s_waitcnt lgkmcnt(0)
	v_add_f32_e32 v230, v230, v231
	v_add_f32_e32 v234, v234, v235
	v_add_f32_e32 v238, v238, v239
	v_add_f32_e32 v242, v242, v243
	ds_bpermute_b32 v231, v172, v230
	ds_bpermute_b32 v235, v172, v234
	ds_bpermute_b32 v239, v172, v238
	ds_bpermute_b32 v243, v172, v242
	s_waitcnt lgkmcnt(0)
	v_add_f32_e32 v230, v230, v231
	v_add_f32_e32 v234, v234, v235
	v_add_f32_e32 v238, v238, v239
	v_add_f32_e32 v242, v242, v243
	v_fmamk_f32 v232, v230, 0x3a800000, v152
	v_fmamk_f32 v236, v234, 0x3a800000, v152
	v_fmamk_f32 v240, v238, 0x3a800000, v152
	v_fmamk_f32 v244, v242, 0x3a800000, v152
	v_rsq_f32_e32 v230, v232
	v_rsq_f32_e32 v234, v236
	v_rsq_f32_e32 v238, v240
	v_rsq_f32_e32 v242, v244
	s_nop 0
	v_mul_f32_e32 v230, 0xbfb8aa3b, v230
	v_mul_f32_e32 v234, 0xbfb8aa3b, v234
	v_mul_f32_e32 v238, 0xbfb8aa3b, v238
	v_mul_f32_e32 v242, 0xbfb8aa3b, v242
	v_pk_mul_f32 v[176:177], v[116:117], v[230:231] op_sel_hi:[1,0]
	v_pk_mul_f32 v[178:179], v[118:119], v[230:231] op_sel_hi:[1,0]
	v_pk_mul_f32 v[180:181], v[112:113], v[230:231] op_sel_hi:[1,0]
	v_pk_mul_f32 v[182:183], v[114:115], v[230:231] op_sel_hi:[1,0]
	v_exp_f32_e32 v176, v176
	v_exp_f32_e32 v177, v177
	v_exp_f32_e32 v178, v178
	v_exp_f32_e32 v179, v179
	v_exp_f32_e32 v180, v180
	v_exp_f32_e32 v181, v181
	v_exp_f32_e32 v182, v182
	v_exp_f32_e32 v183, v183
	v_pk_fma_f32 v[176:177], v[176:177], v[232:233], v[232:233] op_sel_hi:[1,0,0]
	v_pk_fma_f32 v[178:179], v[178:179], v[232:233], v[232:233] op_sel_hi:[1,0,0]
	v_pk_fma_f32 v[180:181], v[180:181], v[232:233], v[232:233] op_sel_hi:[1,0,0]
	v_pk_fma_f32 v[182:183], v[182:183], v[232:233], v[232:233] op_sel_hi:[1,0,0]
	v_rcp_f32_e32 v176, v176
	v_rcp_f32_e32 v177, v177
	v_rcp_f32_e32 v178, v178
	v_rcp_f32_e32 v179, v179
	v_rcp_f32_e32 v180, v180
	v_rcp_f32_e32 v181, v181
	v_rcp_f32_e32 v182, v182
	v_rcp_f32_e32 v183, v183
	v_pk_mul_f32 v[116:117], v[116:117], v[124:125]
	v_pk_mul_f32 v[118:119], v[118:119], v[126:127]
	v_pk_mul_f32 v[112:113], v[112:113], v[120:121]
	v_pk_mul_f32 v[114:115], v[114:115], v[122:123]
	v_pk_mul_f32 v[176:177], v[116:117], v[176:177]
	v_pk_mul_f32 v[178:179], v[118:119], v[178:179]
	v_pk_mul_f32 v[180:181], v[112:113], v[180:181]
	v_pk_mul_f32 v[182:183], v[114:115], v[182:183]
	v_cvt_pk_bf16_f32 v192, v176, v177
	v_cvt_pk_bf16_f32 v193, v178, v179
	v_cvt_pk_bf16_f32 v194, v180, v181
	v_cvt_pk_bf16_f32 v195, v182, v183
	v_mov_b32_e32 v200, v248
	s_cbranch_scc1 .Lwtb3_0
	global_store_dwordx4 v200, v[192:195], s[48:49] sc0 sc1
	s_branch .Lwtd3_0
